# P2: gate-logit GEMM tiles moved from workgroups 32-95 (which also carry 5+5 ple_proj tiles) to workgroups 192-255 (4+4 tiles) to balance the phase
# speedup vs baseline: 1.0003x; 1.0003x over previous
.LBB0_874:
	s_sub_i32 s0, s33, 0xc0
	s_ashr_i32 s1, s0, 31
	s_abs_i32 s0, s0
	s_mul_hi_u32 s4, s0, s34
	s_mul_i32 s4, s4, s19
	s_sub_i32 s0, s0, s4
	s_sub_i32 s4, s0, s19
	s_cmp_ge_u32 s0, s19
	s_cselect_b32 s0, s4, s0
	s_sub_i32 s4, s0, s19
	s_cmp_ge_u32 s0, s19
	s_cselect_b32 s0, s4, s0
	s_xor_b32 s0, s0, s1
	s_sub_i32 s19, s0, s1
	v_mov_b32_e32 v4, v200
	s_mov_b32 s18, 32
	s_cmp_gt_i32 s19, 63
	v_readfirstlane_b32 s6, v4
	s_cbranch_scc1 .LBB0_904
	s_ashr_i32 s33, s19, 31
	s_lshr_b32 s0, s33, 29
	s_add_i32 s7, s19, s0
	s_and_b32 s0, s7, -8
	s_sub_i32 s5, s19, s0
	s_cmp_gt_i32 s5, -1
	s_cbranch_scc0 .LBB0_877
	s_lshl_b32 s4, s5, 3
	s_ashr_i32 s0, s7, 3
	s_cbranch_execz .LBB0_878
	s_branch .LBB0_879
